# EpiResid (P2/P6/P8): first four second-half residual loads issued with the first-half loads into spare VGPRs (removes a second exposed memory latency per tile)
# baseline (speedup 1.0000x reference)
; __device__ __forceinline__ unsigned cvt_pk_bf16(float lo, float hi) { unsigned r; asm volatile("v_cvt_pk_bf16_f32 %0, %1, %2" : "=v"(r) : "v"(lo), "v"(hi)); return r; }
; __device__ __forceinline__ float bf_lo(unsigned w) { return __uint_as_float(w << 16); }
;     __device__ __forceinline__ void operator()(const f32x4 (&acc)[2][2][4][2], const Unit& u, int wr, int wc, int fr, int fq) const {
;     ...
;             f32x4 bf[BASE_F32 ? RB : 1][2][2]; u32x4 bb[BASE_F32 ? 1 : RB][2];
; #pragma unroll
;             for (int mm = 0; mm < RB; ++mm) { const size_t off = (size_t)(row0 + ai * HALF + (mh + mm) * 16) * D_MODEL + col0;
; #pragma unroll
;                 for (int bj = 0; bj < 2; ++bj) {
;                     if (BASE_F32) { bf[mm][bj][0] = *(const f32x4*)(basef + off + bj * HALF); bf[mm][bj][1] = *(const f32x4*)(basef + off + bj * HALF + 4); }
;                     else bb[mm][bj] = *(const u32x4*)(xb + off + bj * HALF);
;                 } }
;             asm volatile("" ::: "memory");
; #pragma unroll
;             for (int mm = 0; mm < RB; ++mm) {
;                 const int m = mh + mm;
;                 const int row = row0 + ai * HALF + m * 16; const size_t off = (size_t)row * D_MODEL + col0; float s = 0.f;
; #pragma unroll
;                 for (int bj = 0; bj < 2; ++bj) {
;                     f32x4 b0, b1;
;                     if (BASE_F32) { b0 = bf[mm][bj][0]; b1 = bf[mm][bj][1]; }
;                     else { const u32x4 w = bb[mm][bj]; b0 = (f32x4){bf_lo(w.x), bf_hi(w.x), bf_lo(w.y), bf_hi(w.y)}; b1 = (f32x4){bf_lo(w.z), bf_hi(w.z), bf_lo(w.w), bf_hi(w.w)}; }
;                     const f32x4 o0 = b0 + acc[ai][bj][m][0] * alpha, o1 = b1 + acc[ai][bj][m][1] * alpha;
;                     if (OUT_F32) { *(f32x4*)(out + off + bj * HALF) = o0; *(f32x4*)(out + off + bj * HALF + 4) = o1; }
;                     else { u32x4 w; w.x = cvt_pk_bf16(o0[0], o0[1]); w.y = cvt_pk_bf16(o0[2], o0[3]); w.z = cvt_pk_bf16(o1[0], o1[1]); w.w = cvt_pk_bf16(o1[2], o1[3]); *(u32x4*)(xb + off + bj * HALF) = w; }
;                     s += ((o0[0] * o0[0] + o0[1] * o0[1]) + (o0[2] * o0[2] + o0[3] * o0[3])) + ((o1[0] * o1[0] + o1[1] * o1[1]) + (o1[2] * o1[2] + o1[3] * o1[3]));
;                 }
;                 if (ssp) { s += __shfl_xor(s, 16); s += __shfl_xor(s, 32); if (fq == 0) ssp[(size_t)row * 16 + u.pn * 4 + wc] = s; }
.LBB0_260:
	v_lshl_or_b32 v166, s16, 8, v186
	v_lshl_add_u32 v168, s33, 8, v184
	v_ashrrev_i32_e32 v167, 31, v166
	v_readlane_b32 s2, v235, 38
	v_lshlrev_b64 v[202:203], 1, v[166:167]
	v_readlane_b32 s3, v235, 39
	v_ashrrev_i32_e32 v169, 31, v168
	v_or_b32_e32 v180, 16, v168
	v_or_b32_e32 v176, 32, v168
	v_lshl_add_u64 v[170:171], s[2:3], 0, v[202:203]
	v_lshlrev_b64 v[204:205], 11, v[168:169]
	v_or_b32_e32 v172, 48, v168
	v_ashrrev_i32_e32 v181, 31, v180
	v_ashrrev_i32_e32 v177, 31, v176
	v_lshl_add_u64 v[128:129], v[170:171], 0, v[204:205]
	v_ashrrev_i32_e32 v173, 31, v172
	v_lshlrev_b64 v[182:183], 11, v[180:181]
	v_lshlrev_b64 v[178:179], 11, v[176:177]
	global_load_dwordx4 v[192:195], v[128:129], off
	global_load_dwordx4 v[198:201], v[128:129], off offset:256
	v_lshlrev_b64 v[174:175], 11, v[172:173]
	v_lshl_add_u64 v[128:129], v[170:171], 0, v[182:183]
	v_lshl_add_u64 v[130:131], v[170:171], 0, v[178:179]
	v_lshl_add_u64 v[206:207], v[170:171], 0, v[174:175]
	global_load_dwordx4 v[148:151], v[128:129], off
	global_load_dwordx4 v[144:147], v[128:129], off offset:256
	global_load_dwordx4 v[140:143], v[130:131], off
	global_load_dwordx4 v[136:139], v[130:131], off offset:256
	global_load_dwordx4 v[132:135], v[206:207], off
	s_nop 0
	global_load_dwordx4 v[128:131], v[206:207], off offset:256
	v_add_u32_e32 v238, 0x80, v168
	v_ashrrev_i32_e32 v239, 31, v238
	v_lshlrev_b64 v[238:239], 11, v[238:239]
	v_lshl_add_u64 v[238:239], v[170:171], 0, v[238:239]
	global_load_dwordx4 v[240:243], v[238:239], off
	global_load_dwordx4 v[244:247], v[238:239], off offset:256
	v_add_u32_e32 v238, 0x90, v168
	v_ashrrev_i32_e32 v239, 31, v238
	v_lshlrev_b64 v[238:239], 11, v[238:239]
	v_lshl_add_u64 v[238:239], v[170:171], 0, v[238:239]
	global_load_dwordx4 v[248:251], v[238:239], off
	global_load_dwordx4 v[252:255], v[238:239], off offset:256
	v_readlane_b32 s30, v235, 42
	v_readlane_b32 s31, v235, 43
	v_lshl_add_u64 v[204:205], s[2:3], 0, v[204:205]
	s_lshl_b32 s26, s16, 2
	v_cndmask_b32_e64 v197, 0, 1, s[30:31]
	v_lshl_add_u64 v[202:203], v[204:205], 0, v[202:203]
	s_ashr_i32 s27, s26, 31
	v_cmp_ne_u32_e64 s[8:9], 1, v197
	s_andn2_b64 vcc, exec, s[30:31]
	s_waitcnt vmcnt(0)
	v_lshlrev_b32_e32 v204, 16, v192
	v_and_b32_e32 v205, 0xffff0000, v192
	v_lshlrev_b32_e32 v192, 16, v193
	v_and_b32_e32 v193, 0xffff0000, v193
	v_lshlrev_b32_e32 v206, 16, v194
	v_and_b32_e32 v207, 0xffff0000, v194
	v_lshlrev_b32_e32 v194, 16, v195
	v_and_b32_e32 v195, 0xffff0000, v195
	v_lshlrev_b32_e32 v208, 16, v198
	v_and_b32_e32 v209, 0xffff0000, v198
	v_lshlrev_b32_e32 v198, 16, v199
	v_and_b32_e32 v199, 0xffff0000, v199
	v_lshlrev_b32_e32 v210, 16, v200
	v_and_b32_e32 v211, 0xffff0000, v200
	v_lshlrev_b32_e32 v200, 16, v201
	v_and_b32_e32 v201, 0xffff0000, v201
	v_pk_fma_f32 v[126:127], v[126:127], 0.5, v[192:193] op_sel_hi:[1,0,1]
	v_pk_fma_f32 v[124:125], v[124:125], 0.5, v[204:205] op_sel_hi:[1,0,1]
	v_pk_fma_f32 v[122:123], v[122:123], 0.5, v[194:195] op_sel_hi:[1,0,1]
	v_pk_fma_f32 v[120:121], v[120:121], 0.5, v[206:207] op_sel_hi:[1,0,1]
	v_pk_fma_f32 v[118:119], v[118:119], 0.5, v[198:199] op_sel_hi:[1,0,1]
	v_pk_fma_f32 v[116:117], v[116:117], 0.5, v[208:209] op_sel_hi:[1,0,1]
	v_pk_fma_f32 v[114:115], v[114:115], 0.5, v[200:201] op_sel_hi:[1,0,1]
	v_pk_fma_f32 v[112:113], v[112:113], 0.5, v[210:211] op_sel_hi:[1,0,1]
	v_cvt_pk_bf16_f32 v192, v124, v125
	v_cvt_pk_bf16_f32 v193, v126, v127
	v_cvt_pk_bf16_f32 v194, v120, v121
	v_cvt_pk_bf16_f32 v195, v122, v123
	global_store_dwordx4 v[202:203], v[192:195], off
	s_nop 1
	v_cvt_pk_bf16_f32 v192, v116, v117
	v_cvt_pk_bf16_f32 v193, v118, v119
	v_cvt_pk_bf16_f32 v194, v112, v113
	v_cvt_pk_bf16_f32 v195, v114, v115
	global_store_dwordx4 v[202:203], v[192:195], off offset:256
	s_cbranch_vccnz .LBB0_264
	v_mul_f32_e32 v113, v113, v113
	v_mul_f32_e32 v125, v125, v125
	v_mul_f32_e32 v121, v121, v121
	v_mul_f32_e32 v117, v117, v117
	v_fmac_f32_e32 v113, v112, v112
	v_mul_f32_e32 v112, v115, v115
	v_fmac_f32_e32 v125, v124, v124
	v_mul_f32_e32 v124, v127, v127
	v_fmac_f32_e32 v121, v120, v120
	v_mul_f32_e32 v120, v123, v123
	v_fmac_f32_e32 v117, v116, v116
	v_mul_f32_e32 v116, v119, v119
	v_fmac_f32_e32 v112, v114, v114
	v_and_b32_e32 v114, 64, v191
	v_fmac_f32_e32 v124, v126, v126
	v_fmac_f32_e32 v120, v122, v122
	v_fmac_f32_e32 v116, v118, v118
	v_add_f32_e32 v112, v113, v112
	v_xor_b32_e32 v113, 16, v191
	v_add_u32_e32 v114, 64, v114
	v_add_f32_e32 v124, v125, v124
	v_add_f32_e32 v120, v121, v120
	v_add_f32_e32 v116, v117, v116
	v_cmp_lt_i32_e32 vcc, v113, v114
	v_add_f32_e32 v120, v124, v120
	v_add_f32_e32 v112, v116, v112
	v_cndmask_b32_e32 v113, v191, v113, vcc
	v_add_f32_e32 v112, v120, v112
	v_lshlrev_b32_e32 v113, 2, v113
	v_mov_b32_e32 v236, v112
	v_mov_b32_e32 v237, v112
	s_nop 1
	v_permlane16_swap_b32_e32 v236, v237
	v_cndmask_b32_e64 v113, v237, v236, s[98:99]
	s_waitcnt lgkmcnt(0)
	v_add_f32_e32 v112, v112, v113
	v_xor_b32_e32 v113, 32, v191
	v_cmp_lt_i32_e32 vcc, v113, v114
	s_nop 1
	v_cndmask_b32_e32 v113, v191, v113, vcc
	v_lshlrev_b32_e32 v113, 2, v113
	v_mov_b32_e32 v236, v112
	v_mov_b32_e32 v237, v112
	s_nop 1
	v_permlane32_swap_b32_e32 v236, v237
	v_cndmask_b32_e64 v113, v237, v236, s[100:101]
	s_and_saveexec_b64 s[2:3], s[4:5]
	s_cbranch_execz .LBB0_263
	v_readlane_b32 s30, v235, 50
	v_lshlrev_b64 v[114:115], 6, v[168:169]
	v_readlane_b32 s31, v235, 51
	s_lshl_b32 s16, s39, 2
	s_waitcnt lgkmcnt(0)
	v_add_f32_e32 v112, v112, v113
	v_lshl_add_u64 v[114:115], s[30:31], 0, v[114:115]
	v_lshl_add_u64 v[114:115], s[26:27], 2, v[114:115]
	v_lshl_add_u64 v[114:115], v[114:115], 0, s[16:17]
	global_store_dword v[114:115], v112, off

; __device__ __forceinline__ unsigned cvt_pk_bf16(float lo, float hi) { unsigned r; asm volatile("v_cvt_pk_bf16_f32 %0, %1, %2" : "=v"(r) : "v"(lo), "v"(hi)); return r; }
; __device__ __forceinline__ float bf_lo(unsigned w) { return __uint_as_float(w << 16); }
; __device__ __forceinline__ float bf_hi(unsigned w) { return __uint_as_float(w & 0xffff0000u); }
;     __device__ __forceinline__ void operator()(const f32x4 (&acc)[2][2][4][2], const Unit& u, int wr, int wc, int fr, int fq) const {
;     ...
;             for (int mm = 0; mm < RB; ++mm) { const size_t off = (size_t)(row0 + ai * HALF + (mh + mm) * 16) * D_MODEL + col0;
; #pragma unroll
;                 for (int bj = 0; bj < 2; ++bj) {
;                     if (BASE_F32) { bf[mm][bj][0] = *(const f32x4*)(basef + off + bj * HALF); bf[mm][bj][1] = *(const f32x4*)(basef + off + bj * HALF + 4); }
;                     else bb[mm][bj] = *(const u32x4*)(xb + off + bj * HALF);
;                 } }
;             asm volatile("" ::: "memory");
; #pragma unroll
;             for (int mm = 0; mm < RB; ++mm) {
;                 const int m = mh + mm;
;                 const int row = row0 + ai * HALF + m * 16; const size_t off = (size_t)row * D_MODEL + col0; float s = 0.f;
; #pragma unroll
;                 for (int bj = 0; bj < 2; ++bj) {
;                     f32x4 b0, b1;
;                     if (BASE_F32) { b0 = bf[mm][bj][0]; b1 = bf[mm][bj][1]; }
;                     else { const u32x4 w = bb[mm][bj]; b0 = (f32x4){bf_lo(w.x), bf_hi(w.x), bf_lo(w.y), bf_hi(w.y)}; b1 = (f32x4){bf_lo(w.z), bf_hi(w.z), bf_lo(w.w), bf_hi(w.w)}; }
;                     const f32x4 o0 = b0 + acc[ai][bj][m][0] * alpha, o1 = b1 + acc[ai][bj][m][1] * alpha;
;                     if (OUT_F32) { *(f32x4*)(out + off + bj * HALF) = o0; *(f32x4*)(out + off + bj * HALF + 4) = o1; }
;                     else { u32x4 w; w.x = cvt_pk_bf16(o0[0], o0[1]); w.y = cvt_pk_bf16(o0[2], o0[3]); w.z = cvt_pk_bf16(o1[0], o1[1]); w.w = cvt_pk_bf16(o1[2], o1[3]); *(u32x4*)(xb + off + bj * HALF) = w; }
;                     s += ((o0[0] * o0[0] + o0[1] * o0[1]) + (o0[2] * o0[2] + o0[3] * o0[3])) + ((o1[0] * o1[0] + o1[1] * o1[1]) + (o1[2] * o1[2] + o1[3] * o1[3]));
;                 }
;                 if (ssp) { s += __shfl_xor(s, 16); s += __shfl_xor(s, 32); if (fq == 0) ssp[(size_t)row * 16 + u.pn * 4 + wc] = s; }
.LBB0_276:
	v_add_u32_e32 v100, 0x80, v168
	v_ashrrev_i32_e32 v101, 31, v100
	v_add_u32_e32 v96, 0x90, v168
	v_add_u32_e32 v92, 0xa0, v168
	v_lshlrev_b64 v[110:111], 11, v[100:101]
	v_add_u32_e32 v88, 0xb0, v168
	v_ashrrev_i32_e32 v97, 31, v96
	v_ashrrev_i32_e32 v93, 31, v92
	s_waitcnt lgkmcnt(0)
	v_lshl_add_u64 v[64:65], v[170:171], 0, v[110:111]
	v_ashrrev_i32_e32 v89, 31, v88
	v_lshlrev_b64 v[98:99], 11, v[96:97]
	v_lshlrev_b64 v[94:95], 11, v[92:93]
	v_lshlrev_b64 v[90:91], 11, v[88:89]
	v_lshl_add_u64 v[64:65], v[170:171], 0, v[98:99]
	v_lshl_add_u64 v[66:67], v[170:171], 0, v[94:95]
	v_lshl_add_u64 v[112:113], v[170:171], 0, v[90:91]
	global_load_dwordx4 v[76:79], v[66:67], off
	global_load_dwordx4 v[72:75], v[66:67], off offset:256
	global_load_dwordx4 v[68:71], v[112:113], off
	s_nop 0
	global_load_dwordx4 v[64:67], v[112:113], off offset:256
	v_readlane_b32 s2, v235, 38
	v_readlane_b32 s3, v235, 39
	s_and_b64 vcc, exec, s[8:9]
	s_waitcnt vmcnt(7)
	v_lshlrev_b32_e32 v112, 16, v240
	v_lshl_add_u64 v[110:111], s[2:3], 0, v[110:111]
	v_and_b32_e32 v113, 0xffff0000, v240
	v_lshlrev_b32_e32 v102, 16, v241
	v_and_b32_e32 v103, 0xffff0000, v241
	v_lshlrev_b32_e32 v114, 16, v242
	v_and_b32_e32 v115, 0xffff0000, v242
	v_lshlrev_b32_e32 v104, 16, v243
	v_and_b32_e32 v105, 0xffff0000, v243
	s_waitcnt vmcnt(6)
	v_lshlrev_b32_e32 v116, 16, v244
	v_and_b32_e32 v117, 0xffff0000, v244
	v_lshlrev_b32_e32 v106, 16, v245
	v_and_b32_e32 v107, 0xffff0000, v245
	v_lshlrev_b32_e32 v118, 16, v246
	v_and_b32_e32 v119, 0xffff0000, v246
	v_lshlrev_b32_e32 v108, 16, v247
	v_and_b32_e32 v109, 0xffff0000, v247
	v_lshl_add_u64 v[110:111], v[166:167], 1, v[110:111]
	v_pk_fma_f32 v[62:63], v[62:63], 0.5, v[102:103] op_sel_hi:[1,0,1]
	v_pk_fma_f32 v[60:61], v[60:61], 0.5, v[112:113] op_sel_hi:[1,0,1]
	v_pk_fma_f32 v[58:59], v[58:59], 0.5, v[104:105] op_sel_hi:[1,0,1]
	v_pk_fma_f32 v[56:57], v[56:57], 0.5, v[114:115] op_sel_hi:[1,0,1]
	v_pk_fma_f32 v[54:55], v[54:55], 0.5, v[106:107] op_sel_hi:[1,0,1]
	v_pk_fma_f32 v[52:53], v[52:53], 0.5, v[116:117] op_sel_hi:[1,0,1]
	v_pk_fma_f32 v[50:51], v[50:51], 0.5, v[108:109] op_sel_hi:[1,0,1]
	v_pk_fma_f32 v[48:49], v[48:49], 0.5, v[118:119] op_sel_hi:[1,0,1]
	v_cvt_pk_bf16_f32 v102, v60, v61
	v_cvt_pk_bf16_f32 v103, v62, v63
	v_cvt_pk_bf16_f32 v104, v56, v57
	v_cvt_pk_bf16_f32 v105, v58, v59
	global_store_dwordx4 v[110:111], v[102:105], off
	s_nop 1
	v_cvt_pk_bf16_f32 v102, v52, v53
	v_cvt_pk_bf16_f32 v103, v54, v55
	v_cvt_pk_bf16_f32 v104, v48, v49
	v_cvt_pk_bf16_f32 v105, v50, v51
	global_store_dwordx4 v[110:111], v[102:105], off offset:256
	s_cbranch_vccnz .LBB0_280
	v_mul_f32_e32 v49, v49, v49
	v_mul_f32_e32 v61, v61, v61
	v_mul_f32_e32 v57, v57, v57
	v_mul_f32_e32 v53, v53, v53
	v_fmac_f32_e32 v49, v48, v48
	v_mul_f32_e32 v48, v51, v51
	v_fmac_f32_e32 v61, v60, v60
	v_mul_f32_e32 v60, v63, v63
	v_fmac_f32_e32 v57, v56, v56
	v_mul_f32_e32 v56, v59, v59
	v_fmac_f32_e32 v53, v52, v52
	v_mul_f32_e32 v52, v55, v55
	v_fmac_f32_e32 v48, v50, v50
	v_and_b32_e32 v50, 64, v191
	v_fmac_f32_e32 v60, v62, v62
	v_fmac_f32_e32 v56, v58, v58
	v_fmac_f32_e32 v52, v54, v54
	v_add_f32_e32 v48, v49, v48
	v_xor_b32_e32 v49, 16, v191
	v_add_u32_e32 v50, 64, v50
	v_add_f32_e32 v60, v61, v60
	v_add_f32_e32 v56, v57, v56
	v_add_f32_e32 v52, v53, v52
	v_cmp_lt_i32_e32 vcc, v49, v50
	v_add_f32_e32 v56, v60, v56
	v_add_f32_e32 v48, v52, v48
	v_cndmask_b32_e32 v49, v191, v49, vcc
	v_add_f32_e32 v48, v56, v48
	v_lshlrev_b32_e32 v49, 2, v49
	v_mov_b32_e32 v236, v48
	v_mov_b32_e32 v237, v48
	s_nop 1
	v_permlane16_swap_b32_e32 v236, v237
	v_cndmask_b32_e64 v49, v237, v236, s[98:99]
	s_waitcnt lgkmcnt(0)
	v_add_f32_e32 v48, v48, v49
	v_xor_b32_e32 v49, 32, v191
	v_cmp_lt_i32_e32 vcc, v49, v50
	s_nop 1
	v_cndmask_b32_e32 v49, v191, v49, vcc
	v_lshlrev_b32_e32 v49, 2, v49
	v_mov_b32_e32 v236, v48
	v_mov_b32_e32 v237, v48
	s_nop 1
	v_permlane32_swap_b32_e32 v236, v237
	v_cndmask_b32_e64 v49, v237, v236, s[100:101]
	s_and_saveexec_b64 s[2:3], s[4:5]
	s_cbranch_execz .LBB0_279
	v_readlane_b32 s30, v235, 50
	v_lshlrev_b64 v[50:51], 6, v[100:101]
	v_readlane_b32 s31, v235, 51
	s_lshl_b32 s16, s39, 2
	s_waitcnt lgkmcnt(0)
	v_add_f32_e32 v48, v48, v49
	v_lshl_add_u64 v[50:51], s[30:31], 0, v[50:51]
	v_lshl_add_u64 v[50:51], s[26:27], 2, v[50:51]
	v_lshl_add_u64 v[50:51], v[50:51], 0, s[16:17]
	global_store_dword v[50:51], v48, off

; __device__ __forceinline__ unsigned cvt_pk_bf16(float lo, float hi) { unsigned r; asm volatile("v_cvt_pk_bf16_f32 %0, %1, %2" : "=v"(r) : "v"(lo), "v"(hi)); return r; }
; __device__ __forceinline__ float bf_lo(unsigned w) { return __uint_as_float(w << 16); }
; __device__ __forceinline__ float bf_hi(unsigned w) { return __uint_as_float(w & 0xffff0000u); }
;     __device__ __forceinline__ void operator()(const f32x4 (&acc)[2][2][4][2], const Unit& u, int wr, int wc, int fr, int fq) const {
;     ...
;             for (int mm = 0; mm < RB; ++mm) {
;                 const int m = mh + mm;
;                 const int row = row0 + ai * HALF + m * 16; const size_t off = (size_t)row * D_MODEL + col0; float s = 0.f;
; #pragma unroll
;                 for (int bj = 0; bj < 2; ++bj) {
;                     f32x4 b0, b1;
;                     if (BASE_F32) { b0 = bf[mm][bj][0]; b1 = bf[mm][bj][1]; }
;                     else { const u32x4 w = bb[mm][bj]; b0 = (f32x4){bf_lo(w.x), bf_hi(w.x), bf_lo(w.y), bf_hi(w.y)}; b1 = (f32x4){bf_lo(w.z), bf_hi(w.z), bf_lo(w.w), bf_hi(w.w)}; }
;                     const f32x4 o0 = b0 + acc[ai][bj][m][0] * alpha, o1 = b1 + acc[ai][bj][m][1] * alpha;
;                     if (OUT_F32) { *(f32x4*)(out + off + bj * HALF) = o0; *(f32x4*)(out + off + bj * HALF + 4) = o1; }
;                     else { u32x4 w; w.x = cvt_pk_bf16(o0[0], o0[1]); w.y = cvt_pk_bf16(o0[2], o0[3]); w.z = cvt_pk_bf16(o1[0], o1[1]); w.w = cvt_pk_bf16(o1[2], o1[3]); *(u32x4*)(xb + off + bj * HALF) = w; }
;                     s += ((o0[0] * o0[0] + o0[1] * o0[1]) + (o0[2] * o0[2] + o0[3] * o0[3])) + ((o1[0] * o1[0] + o1[1] * o1[1]) + (o1[2] * o1[2] + o1[3] * o1[3]));
;                 }
;                 if (ssp) { s += __shfl_xor(s, 16); s += __shfl_xor(s, 32); if (fq == 0) ssp[(size_t)row * 16 + u.pn * 4 + wc] = s; }
.LBB0_280:
	v_readlane_b32 s2, v235, 38
	s_waitcnt vmcnt(7)
	v_lshlrev_b32_e32 v52, 16, v250
	v_and_b32_e32 v53, 0xffff0000, v250
	v_readlane_b32 s3, v235, 39
	v_lshlrev_b32_e32 v48, 16, v248
	s_waitcnt lgkmcnt(0)
	v_and_b32_e32 v49, 0xffff0000, v248
	v_lshlrev_b32_e32 v50, 16, v249
	v_and_b32_e32 v51, 0xffff0000, v249
	v_lshlrev_b32_e32 v54, 16, v251
	v_and_b32_e32 v55, 0xffff0000, v251
	v_pk_fma_f32 v[40:41], v[40:41], 0.5, v[52:53] op_sel_hi:[1,0,1]
	v_lshl_add_u64 v[52:53], s[2:3], 0, v[98:99]
	v_pk_fma_f32 v[46:47], v[46:47], 0.5, v[50:51] op_sel_hi:[1,0,1]
	v_pk_fma_f32 v[44:45], v[44:45], 0.5, v[48:49] op_sel_hi:[1,0,1]
	v_pk_fma_f32 v[42:43], v[42:43], 0.5, v[54:55] op_sel_hi:[1,0,1]
	v_cvt_pk_bf16_f32 v48, v44, v45
	v_cvt_pk_bf16_f32 v49, v46, v47
	v_cvt_pk_bf16_f32 v50, v40, v41
	v_lshl_add_u64 v[52:53], v[166:167], 1, v[52:53]
	v_cvt_pk_bf16_f32 v51, v42, v43
	global_store_dwordx4 v[52:53], v[48:51], off
	s_waitcnt vmcnt(7)
	v_lshlrev_b32_e32 v54, 16, v254
	v_and_b32_e32 v55, 0xffff0000, v254
	v_lshlrev_b32_e32 v48, 16, v252
	v_and_b32_e32 v49, 0xffff0000, v252
	v_lshlrev_b32_e32 v50, 16, v253
	v_and_b32_e32 v51, 0xffff0000, v253
	v_lshlrev_b32_e32 v56, 16, v255
	v_and_b32_e32 v57, 0xffff0000, v255
	v_pk_fma_f32 v[38:39], v[38:39], 0.5, v[50:51] op_sel_hi:[1,0,1]
	v_pk_fma_f32 v[36:37], v[36:37], 0.5, v[48:49] op_sel_hi:[1,0,1]
	v_pk_fma_f32 v[34:35], v[34:35], 0.5, v[56:57] op_sel_hi:[1,0,1]
	v_pk_fma_f32 v[32:33], v[32:33], 0.5, v[54:55] op_sel_hi:[1,0,1]
	s_and_b64 vcc, exec, s[8:9]
	v_cvt_pk_bf16_f32 v48, v36, v37
	v_cvt_pk_bf16_f32 v49, v38, v39
	v_cvt_pk_bf16_f32 v50, v32, v33
	v_cvt_pk_bf16_f32 v51, v34, v35
	global_store_dwordx4 v[52:53], v[48:51], off offset:256
	s_cbranch_vccnz .LBB0_284
	v_mul_f32_e32 v33, v33, v33
	v_mul_f32_e32 v45, v45, v45
	v_mul_f32_e32 v41, v41, v41
	v_mul_f32_e32 v37, v37, v37
	v_fmac_f32_e32 v33, v32, v32
	v_mul_f32_e32 v32, v35, v35
	v_fmac_f32_e32 v45, v44, v44
	v_mul_f32_e32 v44, v47, v47
	v_fmac_f32_e32 v41, v40, v40
	v_mul_f32_e32 v40, v43, v43
	v_fmac_f32_e32 v37, v36, v36
	v_mul_f32_e32 v36, v39, v39
	v_fmac_f32_e32 v32, v34, v34
	v_and_b32_e32 v34, 64, v191
	v_fmac_f32_e32 v44, v46, v46
	v_fmac_f32_e32 v40, v42, v42
	v_fmac_f32_e32 v36, v38, v38
	v_add_f32_e32 v32, v33, v32
	v_xor_b32_e32 v33, 16, v191
	v_add_u32_e32 v34, 64, v34
	v_add_f32_e32 v44, v45, v44
	v_add_f32_e32 v40, v41, v40
	v_add_f32_e32 v36, v37, v36
	v_cmp_lt_i32_e32 vcc, v33, v34
	v_add_f32_e32 v40, v44, v40
	v_add_f32_e32 v32, v36, v32
	v_cndmask_b32_e32 v33, v191, v33, vcc
	v_add_f32_e32 v32, v40, v32
	v_lshlrev_b32_e32 v33, 2, v33
	v_mov_b32_e32 v236, v32
	v_mov_b32_e32 v237, v32
	s_nop 1
	v_permlane16_swap_b32_e32 v236, v237
	v_cndmask_b32_e64 v33, v237, v236, s[98:99]
	s_waitcnt lgkmcnt(0)
	v_add_f32_e32 v32, v32, v33
	v_xor_b32_e32 v33, 32, v191
	v_cmp_lt_i32_e32 vcc, v33, v34
	s_nop 1
	v_cndmask_b32_e32 v33, v191, v33, vcc
	v_lshlrev_b32_e32 v33, 2, v33
	v_mov_b32_e32 v236, v32
	v_mov_b32_e32 v237, v32
	s_nop 1
	v_permlane32_swap_b32_e32 v236, v237
	v_cndmask_b32_e64 v33, v237, v236, s[100:101]
	s_and_saveexec_b64 s[2:3], s[4:5]
	s_cbranch_execz .LBB0_283
	v_readlane_b32 s30, v235, 50
	v_lshlrev_b64 v[34:35], 6, v[96:97]
	v_readlane_b32 s31, v235, 51
	s_lshl_b32 s16, s39, 2
	s_waitcnt lgkmcnt(0)
	v_add_f32_e32 v32, v32, v33
	v_lshl_add_u64 v[34:35], s[30:31], 0, v[34:35]
	v_lshl_add_u64 v[34:35], s[26:27], 2, v[34:35]
	v_lshl_add_u64 v[34:35], v[34:35], 0, s[16:17]
	global_store_dword v[34:35], v32, off

; __device__ __forceinline__ unsigned cvt_pk_bf16(float lo, float hi) { unsigned r; asm volatile("v_cvt_pk_bf16_f32 %0, %1, %2" : "=v"(r) : "v"(lo), "v"(hi)); return r; }
; __device__ __forceinline__ float bf_lo(unsigned w) { return __uint_as_float(w << 16); }
;     __device__ __forceinline__ void operator()(const f32x4 (&acc)[2][2][4][2], const Unit& u, int wr, int wc, int fr, int fq) const {
;     ...
;             f32x4 bf[BASE_F32 ? RB : 1][2][2]; u32x4 bb[BASE_F32 ? 1 : RB][2];
; #pragma unroll
;             for (int mm = 0; mm < RB; ++mm) { const size_t off = (size_t)(row0 + ai * HALF + (mh + mm) * 16) * D_MODEL + col0;
; #pragma unroll
;                 for (int bj = 0; bj < 2; ++bj) {
;                     if (BASE_F32) { bf[mm][bj][0] = *(const f32x4*)(basef + off + bj * HALF); bf[mm][bj][1] = *(const f32x4*)(basef + off + bj * HALF + 4); }
;                     else bb[mm][bj] = *(const u32x4*)(xb + off + bj * HALF);
;                 } }
;             asm volatile("" ::: "memory");
; #pragma unroll
;             for (int mm = 0; mm < RB; ++mm) {
;                 const int m = mh + mm;
;                 const int row = row0 + ai * HALF + m * 16; const size_t off = (size_t)row * D_MODEL + col0; float s = 0.f;
; #pragma unroll
;                 for (int bj = 0; bj < 2; ++bj) {
;                     f32x4 b0, b1;
;                     if (BASE_F32) { b0 = bf[mm][bj][0]; b1 = bf[mm][bj][1]; }
;                     else { const u32x4 w = bb[mm][bj]; b0 = (f32x4){bf_lo(w.x), bf_hi(w.x), bf_lo(w.y), bf_hi(w.y)}; b1 = (f32x4){bf_lo(w.z), bf_hi(w.z), bf_lo(w.w), bf_hi(w.w)}; }
;                     const f32x4 o0 = b0 + acc[ai][bj][m][0] * alpha, o1 = b1 + acc[ai][bj][m][1] * alpha;
;                     if (OUT_F32) { *(f32x4*)(out + off + bj * HALF) = o0; *(f32x4*)(out + off + bj * HALF + 4) = o1; }
;                     else { u32x4 w; w.x = cvt_pk_bf16(o0[0], o0[1]); w.y = cvt_pk_bf16(o0[2], o0[3]); w.z = cvt_pk_bf16(o1[0], o1[1]); w.w = cvt_pk_bf16(o1[2], o1[3]); *(u32x4*)(xb + off + bj * HALF) = w; }
;                     s += ((o0[0] * o0[0] + o0[1] * o0[1]) + (o0[2] * o0[2] + o0[3] * o0[3])) + ((o1[0] * o1[0] + o1[1] * o1[1]) + (o1[2] * o1[2] + o1[3] * o1[3]));
;                 }
;                 if (ssp) { s += __shfl_xor(s, 16); s += __shfl_xor(s, 32); if (fq == 0) ssp[(size_t)row * 16 + u.pn * 4 + wc] = s; }
.LBB0_826:
	v_lshl_or_b32 v166, s12, 8, v186
	v_lshl_add_u32 v168, s45, 8, v184
	v_ashrrev_i32_e32 v167, 31, v166
	v_readlane_b32 s2, v235, 38
	v_lshlrev_b64 v[194:195], 1, v[166:167]
	v_readlane_b32 s3, v235, 39
	v_ashrrev_i32_e32 v169, 31, v168
	v_lshlrev_b64 v[192:193], 11, v[168:169]
	v_lshl_add_u64 v[170:171], s[2:3], 0, v[194:195]
	v_lshl_add_u64 v[128:129], v[170:171], 0, v[192:193]
	global_load_dwordx4 v[198:201], v[128:129], off
	global_load_dwordx4 v[202:205], v[128:129], off offset:256
	v_or_b32_e32 v180, 16, v168
	v_or_b32_e32 v176, 32, v168
	v_or_b32_e32 v172, 48, v168
	v_ashrrev_i32_e32 v181, 31, v180
	v_ashrrev_i32_e32 v177, 31, v176
	v_ashrrev_i32_e32 v173, 31, v172
	v_lshlrev_b64 v[182:183], 11, v[180:181]
	v_lshlrev_b64 v[178:179], 11, v[176:177]
	v_lshlrev_b64 v[174:175], 11, v[172:173]
	v_lshl_add_u64 v[128:129], v[170:171], 0, v[182:183]
	v_lshl_add_u64 v[130:131], v[170:171], 0, v[178:179]
	v_lshl_add_u64 v[206:207], v[170:171], 0, v[174:175]
	global_load_dwordx4 v[148:151], v[128:129], off
	global_load_dwordx4 v[144:147], v[128:129], off offset:256
	global_load_dwordx4 v[140:143], v[130:131], off
	global_load_dwordx4 v[136:139], v[130:131], off offset:256
	global_load_dwordx4 v[132:135], v[206:207], off
	s_nop 0
	global_load_dwordx4 v[128:131], v[206:207], off offset:256
	v_add_u32_e32 v238, 0x80, v168
	v_ashrrev_i32_e32 v239, 31, v238
	v_lshlrev_b64 v[238:239], 11, v[238:239]
	v_lshl_add_u64 v[238:239], v[170:171], 0, v[238:239]
	global_load_dwordx4 v[240:243], v[238:239], off
	global_load_dwordx4 v[244:247], v[238:239], off offset:256
	v_add_u32_e32 v238, 0x90, v168
	v_ashrrev_i32_e32 v239, 31, v238
	v_lshlrev_b64 v[238:239], 11, v[238:239]
	v_lshl_add_u64 v[238:239], v[170:171], 0, v[238:239]
	global_load_dwordx4 v[248:251], v[238:239], off
	global_load_dwordx4 v[252:255], v[238:239], off offset:256
	v_and_b32_e32 v206, 64, v191
	v_xor_b32_e32 v197, 16, v191
	v_add_u32_e32 v206, 64, v206
	v_xor_b32_e32 v207, 32, v191
	v_cmp_lt_i32_e32 vcc, v197, v206
	s_lshl_b32 s8, s12, 2
	s_ashr_i32 s9, s8, 31
	v_cndmask_b32_e32 v197, v191, v197, vcc
	v_cmp_lt_i32_e32 vcc, v207, v206
	s_waitcnt vmcnt(0)
	v_lshlrev_b32_e32 v208, 16, v200
	v_cndmask_b32_e32 v214, v191, v207, vcc
	v_lshl_add_u64 v[206:207], s[2:3], 0, v[192:193]
	v_lshl_add_u64 v[194:195], v[206:207], 0, v[194:195]
	v_lshlrev_b32_e32 v206, 16, v198
	v_and_b32_e32 v207, 0xffff0000, v198
	v_lshlrev_b32_e32 v198, 16, v199
	v_and_b32_e32 v199, 0xffff0000, v199
	v_and_b32_e32 v209, 0xffff0000, v200
	v_lshlrev_b32_e32 v200, 16, v201
	v_and_b32_e32 v201, 0xffff0000, v201
	v_lshlrev_b32_e32 v210, 16, v202
	v_and_b32_e32 v211, 0xffff0000, v202
	v_lshlrev_b32_e32 v202, 16, v203
	v_and_b32_e32 v203, 0xffff0000, v203
	v_lshlrev_b32_e32 v212, 16, v204
	v_and_b32_e32 v213, 0xffff0000, v204
	v_lshlrev_b32_e32 v204, 16, v205
	v_and_b32_e32 v205, 0xffff0000, v205
	v_pk_add_f32 v[126:127], v[126:127], v[198:199]
	v_pk_add_f32 v[124:125], v[124:125], v[206:207]
	v_pk_add_f32 v[122:123], v[122:123], v[200:201]
	v_pk_add_f32 v[120:121], v[120:121], v[208:209]
	v_pk_add_f32 v[118:119], v[118:119], v[202:203]
	v_pk_add_f32 v[116:117], v[116:117], v[210:211]
	v_pk_add_f32 v[198:199], v[114:115], v[204:205]
	v_pk_add_f32 v[200:201], v[112:113], v[212:213]
	v_lshlrev_b32_e32 v192, 2, v197
	v_cvt_pk_bf16_f32 v112, v124, v125
	v_cvt_pk_bf16_f32 v113, v126, v127
	v_mul_f32_e32 v114, v125, v125
	v_mul_f32_e32 v115, v127, v127
	v_mul_f32_e32 v125, v121, v121
	v_mul_f32_e32 v127, v123, v123
	v_mul_f32_e32 v193, v117, v117
	v_mul_f32_e32 v197, v119, v119
	v_mul_f32_e32 v202, v201, v201
	v_mul_f32_e32 v203, v199, v199
	v_fmac_f32_e32 v114, v124, v124
	v_fmac_f32_e32 v115, v126, v126
	v_fmac_f32_e32 v125, v120, v120
	v_fmac_f32_e32 v127, v122, v122
	v_fmac_f32_e32 v193, v116, v116
	v_fmac_f32_e32 v197, v118, v118
	v_fmac_f32_e32 v202, v200, v200
	v_fmac_f32_e32 v203, v198, v198
	v_add_f32_e32 v114, v114, v115
	v_add_f32_e32 v115, v125, v127
	v_add_f32_e32 v124, v193, v197
	v_add_f32_e32 v125, v202, v203
	v_add_f32_e32 v114, v114, v115
	v_add_f32_e32 v115, v124, v125
	v_add_f32_e32 v124, v114, v115
	v_mov_b32_e32 v236, v124
	v_mov_b32_e32 v237, v124
	s_nop 1
	v_permlane16_swap_b32_e32 v236, v237
	v_cndmask_b32_e64 v125, v237, v236, s[98:99]
	v_cvt_pk_bf16_f32 v114, v120, v121
	v_cvt_pk_bf16_f32 v115, v122, v123
	global_store_dwordx4 v[194:195], v[112:115], off
	v_cvt_pk_bf16_f32 v116, v116, v117
	v_cvt_pk_bf16_f32 v117, v118, v119
	v_cvt_pk_bf16_f32 v118, v200, v201
	v_cvt_pk_bf16_f32 v119, v198, v199
	global_store_dwordx4 v[194:195], v[116:119], off offset:256
	s_waitcnt lgkmcnt(0)
	v_add_f32_e32 v113, v124, v125
	v_lshlrev_b32_e32 v112, 2, v214
	v_mov_b32_e32 v236, v113
	v_mov_b32_e32 v237, v113
	s_nop 1
	v_permlane32_swap_b32_e32 v236, v237
	v_cndmask_b32_e64 v114, v237, v236, s[100:101]
	s_and_saveexec_b64 s[2:3], s[4:5]
	s_cbranch_execz .LBB0_828
	v_lshlrev_b64 v[116:117], 6, v[168:169]
	v_lshl_add_u64 v[116:117], s[10:11], 0, v[116:117]
	v_lshl_add_u64 v[116:117], s[8:9], 2, v[116:117]
	s_lshl_b32 s12, s36, 2
	v_lshl_add_u64 v[116:117], v[116:117], 0, s[12:13]
	s_waitcnt lgkmcnt(0)
	v_add_f32_e32 v113, v113, v114
	global_store_dword v[116:117], v113, off

; __device__ __forceinline__ unsigned cvt_pk_bf16(float lo, float hi) { unsigned r; asm volatile("v_cvt_pk_bf16_f32 %0, %1, %2" : "=v"(r) : "v"(lo), "v"(hi)); return r; }
; __device__ __forceinline__ float bf_lo(unsigned w) { return __uint_as_float(w << 16); }
; __device__ __forceinline__ float bf_hi(unsigned w) { return __uint_as_float(w & 0xffff0000u); }
;     __device__ __forceinline__ void operator()(const f32x4 (&acc)[2][2][4][2], const Unit& u, int wr, int wc, int fr, int fq) const {
;     ...
;             for (int mm = 0; mm < RB; ++mm) { const size_t off = (size_t)(row0 + ai * HALF + (mh + mm) * 16) * D_MODEL + col0;
; #pragma unroll
;                 for (int bj = 0; bj < 2; ++bj) {
;                     if (BASE_F32) { bf[mm][bj][0] = *(const f32x4*)(basef + off + bj * HALF); bf[mm][bj][1] = *(const f32x4*)(basef + off + bj * HALF + 4); }
;                     else bb[mm][bj] = *(const u32x4*)(xb + off + bj * HALF);
;                 } }
;             asm volatile("" ::: "memory");
; #pragma unroll
;             for (int mm = 0; mm < RB; ++mm) {
;                 const int m = mh + mm;
;                 const int row = row0 + ai * HALF + m * 16; const size_t off = (size_t)row * D_MODEL + col0; float s = 0.f;
; #pragma unroll
;                 for (int bj = 0; bj < 2; ++bj) {
;                     f32x4 b0, b1;
;                     if (BASE_F32) { b0 = bf[mm][bj][0]; b1 = bf[mm][bj][1]; }
;                     else { const u32x4 w = bb[mm][bj]; b0 = (f32x4){bf_lo(w.x), bf_hi(w.x), bf_lo(w.y), bf_hi(w.y)}; b1 = (f32x4){bf_lo(w.z), bf_hi(w.z), bf_lo(w.w), bf_hi(w.w)}; }
;                     const f32x4 o0 = b0 + acc[ai][bj][m][0] * alpha, o1 = b1 + acc[ai][bj][m][1] * alpha;
;                     if (OUT_F32) { *(f32x4*)(out + off + bj * HALF) = o0; *(f32x4*)(out + off + bj * HALF + 4) = o1; }
;                     else { u32x4 w; w.x = cvt_pk_bf16(o0[0], o0[1]); w.y = cvt_pk_bf16(o0[2], o0[3]); w.z = cvt_pk_bf16(o1[0], o1[1]); w.w = cvt_pk_bf16(o1[2], o1[3]); *(u32x4*)(xb + off + bj * HALF) = w; }
;                     s += ((o0[0] * o0[0] + o0[1] * o0[1]) + (o0[2] * o0[2] + o0[3] * o0[3])) + ((o1[0] * o1[0] + o1[1] * o1[1]) + (o1[2] * o1[2] + o1[3] * o1[3]));
;                 }
;                 if (ssp) { s += __shfl_xor(s, 16); s += __shfl_xor(s, 32); if (fq == 0) ssp[(size_t)row * 16 + u.pn * 4 + wc] = s; }
.LBB0_834:
	s_or_b64 exec, exec, s[2:3]
	v_add_u32_e32 v100, 0x80, v168
	v_ashrrev_i32_e32 v101, 31, v100
	v_lshlrev_b64 v[110:111], 11, v[100:101]
	s_waitcnt lgkmcnt(0)
	v_lshl_add_u64 v[64:65], v[170:171], 0, v[110:111]
	v_add_u32_e32 v96, 0x90, v168
	v_add_u32_e32 v92, 0xa0, v168
	v_add_u32_e32 v88, 0xb0, v168
	v_ashrrev_i32_e32 v97, 31, v96
	v_ashrrev_i32_e32 v93, 31, v92
	v_ashrrev_i32_e32 v89, 31, v88
	v_lshlrev_b64 v[98:99], 11, v[96:97]
	v_lshlrev_b64 v[94:95], 11, v[92:93]
	v_lshlrev_b64 v[90:91], 11, v[88:89]
	v_lshl_add_u64 v[64:65], v[170:171], 0, v[98:99]
	v_lshl_add_u64 v[66:67], v[170:171], 0, v[94:95]
	v_lshl_add_u64 v[114:115], v[170:171], 0, v[90:91]
	global_load_dwordx4 v[76:79], v[66:67], off
	global_load_dwordx4 v[72:75], v[66:67], off offset:256
	global_load_dwordx4 v[68:71], v[114:115], off
	s_nop 0
	global_load_dwordx4 v[64:67], v[114:115], off offset:256
	v_readlane_b32 s2, v235, 38
	v_readlane_b32 s3, v235, 39
	s_waitcnt vmcnt(7)
	v_lshlrev_b32_e32 v114, 16, v240
	v_and_b32_e32 v115, 0xffff0000, v240
	v_lshlrev_b32_e32 v102, 16, v241
	v_and_b32_e32 v103, 0xffff0000, v241
	v_lshlrev_b32_e32 v116, 16, v242
	v_and_b32_e32 v117, 0xffff0000, v242
	v_lshlrev_b32_e32 v104, 16, v243
	v_and_b32_e32 v105, 0xffff0000, v243
	s_waitcnt vmcnt(6)
	v_lshlrev_b32_e32 v118, 16, v244
	v_and_b32_e32 v119, 0xffff0000, v244
	v_lshlrev_b32_e32 v106, 16, v245
	v_and_b32_e32 v107, 0xffff0000, v245
	v_lshlrev_b32_e32 v120, 16, v246
	v_and_b32_e32 v121, 0xffff0000, v246
	v_lshlrev_b32_e32 v108, 16, v247
	v_and_b32_e32 v109, 0xffff0000, v247
	v_pk_add_f32 v[62:63], v[62:63], v[102:103]
	v_pk_add_f32 v[60:61], v[60:61], v[114:115]
	v_pk_add_f32 v[58:59], v[58:59], v[104:105]
	v_pk_add_f32 v[56:57], v[56:57], v[116:117]
	v_pk_add_f32 v[54:55], v[54:55], v[106:107]
	v_pk_add_f32 v[52:53], v[52:53], v[118:119]
	v_pk_add_f32 v[102:103], v[50:51], v[108:109]
	v_pk_add_f32 v[104:105], v[48:49], v[120:121]
	v_cvt_pk_bf16_f32 v48, v60, v61
	v_cvt_pk_bf16_f32 v49, v62, v63
	v_cvt_pk_bf16_f32 v50, v56, v57
	v_cvt_pk_bf16_f32 v51, v58, v59
	v_mul_f32_e32 v61, v61, v61
	v_mul_f32_e32 v63, v63, v63
	v_mul_f32_e32 v57, v57, v57
	v_mul_f32_e32 v59, v59, v59
	v_mul_f32_e32 v106, v53, v53
	v_mul_f32_e32 v107, v55, v55
	v_mul_f32_e32 v108, v105, v105
	v_mul_f32_e32 v109, v103, v103
	v_fmac_f32_e32 v61, v60, v60
	v_fmac_f32_e32 v63, v62, v62
	v_fmac_f32_e32 v57, v56, v56
	v_fmac_f32_e32 v59, v58, v58
	v_fmac_f32_e32 v106, v52, v52
	v_fmac_f32_e32 v107, v54, v54
	v_fmac_f32_e32 v108, v104, v104
	v_fmac_f32_e32 v109, v102, v102
	v_add_f32_e32 v56, v61, v63
	v_add_f32_e32 v57, v57, v59
	v_add_f32_e32 v58, v106, v107
	v_add_f32_e32 v59, v108, v109
	v_add_f32_e32 v56, v56, v57
	v_add_f32_e32 v57, v58, v59
	v_add_f32_e32 v58, v56, v57
	v_mov_b32_e32 v236, v58
	v_mov_b32_e32 v237, v58
	s_nop 1
	v_permlane16_swap_b32_e32 v236, v237
	v_cndmask_b32_e64 v59, v237, v236, s[98:99]
	v_lshl_add_u64 v[56:57], s[2:3], 0, v[110:111]
	v_lshl_add_u64 v[56:57], v[166:167], 1, v[56:57]
	global_store_dwordx4 v[56:57], v[48:51], off
	s_waitcnt lgkmcnt(0)
	s_nop 0
	v_add_f32_e32 v48, v58, v59
	v_mov_b32_e32 v236, v48
	v_mov_b32_e32 v237, v48
	s_nop 1
	v_permlane32_swap_b32_e32 v236, v237
	v_cndmask_b32_e64 v49, v237, v236, s[100:101]
	v_cvt_pk_bf16_f32 v50, v52, v53
	v_cvt_pk_bf16_f32 v51, v54, v55
	v_cvt_pk_bf16_f32 v52, v104, v105
	v_cvt_pk_bf16_f32 v53, v102, v103
	global_store_dwordx4 v[56:57], v[50:53], off offset:256
	s_and_saveexec_b64 s[2:3], s[4:5]
	s_cbranch_execz .LBB0_836
	v_lshlrev_b64 v[50:51], 6, v[100:101]
	v_lshl_add_u64 v[50:51], s[10:11], 0, v[50:51]
	v_lshl_add_u64 v[50:51], s[8:9], 2, v[50:51]
	s_lshl_b32 s12, s36, 2
	v_lshl_add_u64 v[50:51], v[50:51], 0, s[12:13]
	s_waitcnt lgkmcnt(0)
	v_add_f32_e32 v48, v48, v49
	global_store_dword v[50:51], v48, off
.LBB0_836:
	s_or_b64 exec, exec, s[2:3]
	s_waitcnt vmcnt(7)
	v_lshlrev_b32_e32 v48, 16, v248
	s_waitcnt lgkmcnt(0)
	v_and_b32_e32 v49, 0xffff0000, v248
	v_lshlrev_b32_e32 v50, 16, v249
	v_and_b32_e32 v51, 0xffff0000, v249
	v_lshlrev_b32_e32 v54, 16, v251
	v_and_b32_e32 v55, 0xffff0000, v251
	v_pk_add_f32 v[46:47], v[46:47], v[50:51]
	v_pk_add_f32 v[44:45], v[44:45], v[48:49]
	v_pk_add_f32 v[48:49], v[42:43], v[54:55]
	s_waitcnt vmcnt(6)
	v_lshlrev_b32_e32 v54, 16, v253
	v_and_b32_e32 v55, 0xffff0000, v253
	v_lshlrev_b32_e32 v56, 16, v254
	v_and_b32_e32 v57, 0xffff0000, v254
	v_lshlrev_b32_e32 v52, 16, v250
	v_and_b32_e32 v53, 0xffff0000, v250
	v_pk_add_f32 v[38:39], v[38:39], v[54:55]
	v_pk_add_f32 v[54:55], v[32:33], v[56:57]
	v_mul_f32_e32 v32, v45, v45
	v_mul_f32_e32 v33, v47, v47
	v_pk_add_f32 v[50:51], v[40:41], v[52:53]
	v_lshlrev_b32_e32 v52, 16, v252
	v_and_b32_e32 v53, 0xffff0000, v252
	v_lshlrev_b32_e32 v58, 16, v255
	v_and_b32_e32 v59, 0xffff0000, v255
	v_fmac_f32_e32 v32, v44, v44
	v_fmac_f32_e32 v33, v46, v46
	v_pk_add_f32 v[36:37], v[36:37], v[52:53]
	v_pk_add_f32 v[52:53], v[34:35], v[58:59]
	v_add_f32_e32 v32, v32, v33
	v_mul_f32_e32 v33, v51, v51
	v_mul_f32_e32 v34, v49, v49
	v_fmac_f32_e32 v33, v50, v50
	v_fmac_f32_e32 v34, v48, v48
	v_add_f32_e32 v33, v33, v34
	v_add_f32_e32 v32, v32, v33
	v_mul_f32_e32 v33, v37, v37
	v_mul_f32_e32 v34, v39, v39
	v_fmac_f32_e32 v33, v36, v36
	v_fmac_f32_e32 v34, v38, v38
	v_add_f32_e32 v33, v33, v34
	v_mul_f32_e32 v34, v55, v55
	v_mul_f32_e32 v35, v53, v53
	v_fmac_f32_e32 v34, v54, v54
	v_fmac_f32_e32 v35, v52, v52
	v_add_f32_e32 v34, v34, v35
	v_add_f32_e32 v33, v33, v34
	v_add_f32_e32 v35, v32, v33
	v_cvt_pk_bf16_f32 v40, v44, v45
	v_cvt_pk_bf16_f32 v41, v46, v47
	v_mov_b32_e32 v236, v35
	v_mov_b32_e32 v237, v35
	s_nop 1
	v_permlane16_swap_b32_e32 v236, v237
	v_cndmask_b32_e64 v46, v237, v236, s[98:99]
	v_readlane_b32 s2, v235, 38
	v_readlane_b32 s3, v235, 39
	v_cvt_pk_bf16_f32 v42, v50, v51
	v_cvt_pk_bf16_f32 v43, v48, v49
	s_nop 1
	v_lshl_add_u64 v[32:33], s[2:3], 0, v[98:99]
	v_lshl_add_u64 v[44:45], v[166:167], 1, v[32:33]
	s_waitcnt lgkmcnt(0)
	v_add_f32_e32 v32, v35, v46
	v_mov_b32_e32 v236, v32
	v_mov_b32_e32 v237, v32
	s_nop 1
	v_permlane32_swap_b32_e32 v236, v237
	v_cndmask_b32_e64 v33, v237, v236, s[100:101]
	global_store_dwordx4 v[44:45], v[40:43], off
	v_cvt_pk_bf16_f32 v34, v36, v37
	v_cvt_pk_bf16_f32 v35, v38, v39
	v_cvt_pk_bf16_f32 v36, v54, v55
	v_cvt_pk_bf16_f32 v37, v52, v53
	global_store_dwordx4 v[44:45], v[34:37], off offset:256
	s_and_saveexec_b64 s[2:3], s[4:5]
	s_cbranch_execz .LBB0_838
	v_lshlrev_b64 v[34:35], 6, v[96:97]
	v_lshl_add_u64 v[34:35], s[10:11], 0, v[34:35]
	v_lshl_add_u64 v[34:35], s[8:9], 2, v[34:35]
	s_lshl_b32 s12, s36, 2
	v_lshl_add_u64 v[34:35], v[34:35], 0, s[12:13]
	s_waitcnt lgkmcnt(0)
	v_add_f32_e32 v32, v32, v33
	global_store_dword v[34:35], v32, off

; __device__ __forceinline__ unsigned cvt_pk_bf16(float lo, float hi) { unsigned r; asm volatile("v_cvt_pk_bf16_f32 %0, %1, %2" : "=v"(r) : "v"(lo), "v"(hi)); return r; }
; __device__ __forceinline__ float bf_lo(unsigned w) { return __uint_as_float(w << 16); }
; __device__ __forceinline__ float bf_hi(unsigned w) { return __uint_as_float(w & 0xffff0000u); }
;     __device__ __forceinline__ void operator()(const f32x4 (&acc)[2][2][4][2], const Unit& u, int wr, int wc, int fr, int fq) const {
;     ...
;             for (int mm = 0; mm < RB; ++mm) { const size_t off = (size_t)(row0 + ai * HALF + (mh + mm) * 16) * D_MODEL + col0;
; #pragma unroll
;                 for (int bj = 0; bj < 2; ++bj) {
;                     if (BASE_F32) { bf[mm][bj][0] = *(const f32x4*)(basef + off + bj * HALF); bf[mm][bj][1] = *(const f32x4*)(basef + off + bj * HALF + 4); }
;                     else bb[mm][bj] = *(const u32x4*)(xb + off + bj * HALF);
;                 } }
;             asm volatile("" ::: "memory");
; #pragma unroll
;             for (int mm = 0; mm < RB; ++mm) {
;                 const int m = mh + mm;
;                 const int row = row0 + ai * HALF + m * 16; const size_t off = (size_t)row * D_MODEL + col0; float s = 0.f;
; #pragma unroll
;                 for (int bj = 0; bj < 2; ++bj) {
;                     f32x4 b0, b1;
;                     if (BASE_F32) { b0 = bf[mm][bj][0]; b1 = bf[mm][bj][1]; }
;                     else { const u32x4 w = bb[mm][bj]; b0 = (f32x4){bf_lo(w.x), bf_hi(w.x), bf_lo(w.y), bf_hi(w.y)}; b1 = (f32x4){bf_lo(w.z), bf_hi(w.z), bf_lo(w.w), bf_hi(w.w)}; }
;                     const f32x4 o0 = b0 + acc[ai][bj][m][0] * alpha, o1 = b1 + acc[ai][bj][m][1] * alpha;
;                     if (OUT_F32) { *(f32x4*)(out + off + bj * HALF) = o0; *(f32x4*)(out + off + bj * HALF + 4) = o1; }
;                     else { u32x4 w; w.x = cvt_pk_bf16(o0[0], o0[1]); w.y = cvt_pk_bf16(o0[2], o0[3]); w.z = cvt_pk_bf16(o1[0], o1[1]); w.w = cvt_pk_bf16(o1[2], o1[3]); *(u32x4*)(xb + off + bj * HALF) = w; }
;                     s += ((o0[0] * o0[0] + o0[1] * o0[1]) + (o0[2] * o0[2] + o0[3] * o0[3])) + ((o1[0] * o1[0] + o1[1] * o1[1]) + (o1[2] * o1[2] + o1[3] * o1[3]));
;                 }
;                 if (ssp) { s += __shfl_xor(s, 16); s += __shfl_xor(s, 32); if (fq == 0) ssp[(size_t)row * 16 + u.pn * 4 + wc] = s; }
.LBB0_1180:
	v_lshl_add_u32 v176, s42, 8, v197
	v_lshl_or_b32 v174, s43, 8, v199
	v_readlane_b32 s2, v235, 38
	v_ashrrev_i32_e32 v175, 31, v174
	v_readlane_b32 s3, v235, 39
	v_ashrrev_i32_e32 v177, 31, v176
	v_lshlrev_b64 v[128:129], 11, v[176:177]
	v_lshl_add_u64 v[194:195], v[174:175], 1, s[2:3]
	v_lshl_add_u64 v[128:129], v[194:195], 0, v[128:129]
	global_load_dwordx4 v[178:181], v[128:129], off
	global_load_dwordx4 v[182:185], v[128:129], off offset:256
	v_or_b32_e32 v172, 16, v176
	v_or_b32_e32 v170, 32, v176
	v_or_b32_e32 v168, 48, v176
	v_ashrrev_i32_e32 v173, 31, v172
	v_ashrrev_i32_e32 v171, 31, v170
	v_ashrrev_i32_e32 v169, 31, v168
	v_lshlrev_b64 v[128:129], 11, v[172:173]
	v_lshlrev_b64 v[130:131], 11, v[170:171]
	v_lshlrev_b64 v[132:133], 11, v[168:169]
	v_lshl_add_u64 v[128:129], v[194:195], 0, v[128:129]
	v_lshl_add_u64 v[130:131], v[194:195], 0, v[130:131]
	v_lshl_add_u64 v[186:187], v[194:195], 0, v[132:133]
	global_load_dwordx4 v[148:151], v[128:129], off
	global_load_dwordx4 v[144:147], v[128:129], off offset:256
	global_load_dwordx4 v[140:143], v[130:131], off
	global_load_dwordx4 v[136:139], v[130:131], off offset:256
	global_load_dwordx4 v[132:135], v[186:187], off
	s_nop 0
	global_load_dwordx4 v[128:131], v[186:187], off offset:256
	v_add_u32_e32 v238, 0x80, v176
	v_ashrrev_i32_e32 v239, 31, v238
	v_lshlrev_b64 v[238:239], 11, v[238:239]
	v_lshl_add_u64 v[238:239], v[194:195], 0, v[238:239]
	global_load_dwordx4 v[240:243], v[238:239], off
	global_load_dwordx4 v[244:247], v[238:239], off offset:256
	v_add_u32_e32 v238, 0x90, v176
	v_ashrrev_i32_e32 v239, 31, v238
	v_lshlrev_b64 v[238:239], 11, v[238:239]
	v_lshl_add_u64 v[238:239], v[194:195], 0, v[238:239]
	global_load_dwordx4 v[248:251], v[238:239], off
	global_load_dwordx4 v[252:255], v[238:239], off offset:256
	v_and_b32_e32 v187, 64, v203
	v_xor_b32_e32 v186, 16, v203
	v_add_u32_e32 v207, 64, v187
	v_cmp_lt_i32_e32 vcc, v186, v207
	v_xor_b32_e32 v206, 32, v203
	s_lshl_b32 s2, s43, 2
	v_cndmask_b32_e32 v186, v203, v186, vcc
	v_lshlrev_b32_e32 v205, 2, v186
	v_cmp_lt_i32_e32 vcc, v206, v207
	s_ashr_i32 s3, s2, 31
	s_lshl_b64 s[2:3], s[2:3], 2
	s_add_u32 s2, s36, s2
	s_addc_u32 s3, s37, s3
	s_waitcnt vmcnt(0)
	v_lshlrev_b32_e32 v186, 16, v178
	v_and_b32_e32 v187, 0xffff0000, v178
	v_lshlrev_b32_e32 v178, 16, v179
	v_and_b32_e32 v179, 0xffff0000, v179
	v_lshlrev_b32_e32 v188, 16, v180
	v_and_b32_e32 v189, 0xffff0000, v180
	v_lshlrev_b32_e32 v180, 16, v181
	v_and_b32_e32 v181, 0xffff0000, v181
	v_lshlrev_b32_e32 v190, 16, v182
	v_and_b32_e32 v191, 0xffff0000, v182
	v_lshlrev_b32_e32 v182, 16, v183
	v_and_b32_e32 v183, 0xffff0000, v183
	v_lshlrev_b32_e32 v192, 16, v184
	v_and_b32_e32 v193, 0xffff0000, v184
	v_lshlrev_b32_e32 v184, 16, v185
	v_and_b32_e32 v185, 0xffff0000, v185
	v_pk_fma_f32 v[126:127], v[126:127], 0.5, v[178:179] op_sel_hi:[1,0,1]
	v_pk_fma_f32 v[124:125], v[124:125], 0.5, v[186:187] op_sel_hi:[1,0,1]
	v_pk_fma_f32 v[122:123], v[122:123], 0.5, v[180:181] op_sel_hi:[1,0,1]
	v_pk_fma_f32 v[120:121], v[120:121], 0.5, v[188:189] op_sel_hi:[1,0,1]
	v_pk_fma_f32 v[118:119], v[118:119], 0.5, v[182:183] op_sel_hi:[1,0,1]
	v_pk_fma_f32 v[116:117], v[116:117], 0.5, v[190:191] op_sel_hi:[1,0,1]
	v_pk_fma_f32 v[114:115], v[114:115], 0.5, v[184:185] op_sel_hi:[1,0,1]
	v_pk_fma_f32 v[112:113], v[112:113], 0.5, v[192:193] op_sel_hi:[1,0,1]
	v_mul_f32_e32 v178, v125, v125
	v_mul_f32_e32 v179, v127, v127
	v_mul_f32_e32 v180, v121, v121
	v_mul_f32_e32 v181, v123, v123
	v_mul_f32_e32 v182, v117, v117
	v_mul_f32_e32 v183, v119, v119
	v_mul_f32_e32 v184, v113, v113
	v_mul_f32_e32 v185, v115, v115
	v_fmac_f32_e32 v178, v124, v124
	v_fmac_f32_e32 v179, v126, v126
	v_fmac_f32_e32 v180, v120, v120
	v_fmac_f32_e32 v181, v122, v122
	v_fmac_f32_e32 v182, v116, v116
	v_fmac_f32_e32 v183, v118, v118
	v_fmac_f32_e32 v184, v112, v112
	v_fmac_f32_e32 v185, v114, v114
	v_add_f32_e32 v178, v178, v179
	v_add_f32_e32 v179, v180, v181
	v_add_f32_e32 v180, v182, v183
	v_add_f32_e32 v181, v184, v185
	v_add_f32_e32 v178, v178, v179
	v_add_f32_e32 v179, v180, v181
	v_add_f32_e32 v178, v178, v179
	v_mov_b32_e32 v236, v178
	v_mov_b32_e32 v237, v178
	s_nop 1
	v_permlane16_swap_b32_e32 v236, v237
	v_cndmask_b32_e64 v179, v237, v236, s[98:99]
	v_cndmask_b32_e32 v180, v203, v206, vcc
	v_lshlrev_b32_e32 v206, 2, v180
	v_lshlrev_b64 v[186:187], 6, v[176:177]
	s_waitcnt lgkmcnt(0)
	v_add_f32_e32 v178, v178, v179
	v_mov_b32_e32 v236, v178
	v_mov_b32_e32 v237, v178
	s_nop 1
	v_permlane32_swap_b32_e32 v236, v237
	v_cndmask_b32_e64 v179, v237, v236, s[100:101]
	s_and_saveexec_b64 s[20:21], s[0:1]
	s_cbranch_execz .LBB0_1182
	s_waitcnt lgkmcnt(0)
	v_add_f32_e32 v180, v178, v179
	v_lshl_add_u64 v[178:179], s[2:3], 0, v[186:187]
	global_store_dword v[178:179], v180, off

; __device__ __forceinline__ unsigned cvt_pk_bf16(float lo, float hi) { unsigned r; asm volatile("v_cvt_pk_bf16_f32 %0, %1, %2" : "=v"(r) : "v"(lo), "v"(hi)); return r; }
; __device__ __forceinline__ float bf_lo(unsigned w) { return __uint_as_float(w << 16); }
; __device__ __forceinline__ float bf_hi(unsigned w) { return __uint_as_float(w & 0xffff0000u); }
;     __device__ __forceinline__ void operator()(const f32x4 (&acc)[2][2][4][2], const Unit& u, int wr, int wc, int fr, int fq) const {
;     ...
;             for (int mm = 0; mm < RB; ++mm) {
;                 const int m = mh + mm;
;                 const int row = row0 + ai * HALF + m * 16; const size_t off = (size_t)row * D_MODEL + col0; float s = 0.f;
; #pragma unroll
;                 for (int bj = 0; bj < 2; ++bj) {
;                     f32x4 b0, b1;
;                     if (BASE_F32) { b0 = bf[mm][bj][0]; b1 = bf[mm][bj][1]; }
;                     else { const u32x4 w = bb[mm][bj]; b0 = (f32x4){bf_lo(w.x), bf_hi(w.x), bf_lo(w.y), bf_hi(w.y)}; b1 = (f32x4){bf_lo(w.z), bf_hi(w.z), bf_lo(w.w), bf_hi(w.w)}; }
;                     const f32x4 o0 = b0 + acc[ai][bj][m][0] * alpha, o1 = b1 + acc[ai][bj][m][1] * alpha;
;                     if (OUT_F32) { *(f32x4*)(out + off + bj * HALF) = o0; *(f32x4*)(out + off + bj * HALF + 4) = o1; }
;                     else { u32x4 w; w.x = cvt_pk_bf16(o0[0], o0[1]); w.y = cvt_pk_bf16(o0[2], o0[3]); w.z = cvt_pk_bf16(o1[0], o1[1]); w.w = cvt_pk_bf16(o1[2], o1[3]); *(u32x4*)(xb + off + bj * HALF) = w; }
;                     s += ((o0[0] * o0[0] + o0[1] * o0[1]) + (o0[2] * o0[2] + o0[3] * o0[3])) + ((o1[0] * o1[0] + o1[1] * o1[1]) + (o1[2] * o1[2] + o1[3] * o1[3]));
;                 }
;                 if (ssp) { s += __shfl_xor(s, 16); s += __shfl_xor(s, 32); if (fq == 0) ssp[(size_t)row * 16 + u.pn * 4 + wc] = s; }
.LBB0_1188:
	s_or_b64 exec, exec, s[20:21]
	v_add_u32_e32 v184, 0x80, v176
	v_ashrrev_i32_e32 v185, 31, v184
	s_waitcnt lgkmcnt(0)
	v_lshlrev_b64 v[64:65], 11, v[184:185]
	v_lshl_add_u64 v[64:65], v[194:195], 0, v[64:65]
	v_add_u32_e32 v128, 0x90, v176
	v_add_u32_e32 v92, 0xa0, v176
	v_add_u32_e32 v88, 0xb0, v176
	v_ashrrev_i32_e32 v129, 31, v128
	v_ashrrev_i32_e32 v93, 31, v92
	v_ashrrev_i32_e32 v89, 31, v88
	v_lshlrev_b64 v[64:65], 11, v[128:129]
	v_lshlrev_b64 v[66:67], 11, v[92:93]
	v_lshlrev_b64 v[68:69], 11, v[88:89]
	v_lshl_add_u64 v[64:65], v[194:195], 0, v[64:65]
	v_lshl_add_u64 v[66:67], v[194:195], 0, v[66:67]
	v_lshl_add_u64 v[194:195], v[194:195], 0, v[68:69]
	global_load_dwordx4 v[76:79], v[66:67], off
	global_load_dwordx4 v[72:75], v[66:67], off offset:256
	global_load_dwordx4 v[68:71], v[194:195], off
	s_nop 0
	global_load_dwordx4 v[64:67], v[194:195], off offset:256
	s_waitcnt vmcnt(7)
	v_lshlrev_b32_e32 v194, 16, v240
	v_and_b32_e32 v195, 0xffff0000, v240
	v_lshlrev_b32_e32 v208, 16, v241
	v_and_b32_e32 v209, 0xffff0000, v241
	v_lshlrev_b32_e32 v216, 16, v242
	v_and_b32_e32 v217, 0xffff0000, v242
	v_lshlrev_b32_e32 v210, 16, v243
	v_and_b32_e32 v211, 0xffff0000, v243
	s_waitcnt vmcnt(6)
	v_lshlrev_b32_e32 v218, 16, v244
	v_and_b32_e32 v219, 0xffff0000, v244
	v_lshlrev_b32_e32 v212, 16, v245
	v_and_b32_e32 v213, 0xffff0000, v245
	v_lshlrev_b32_e32 v220, 16, v246
	v_and_b32_e32 v221, 0xffff0000, v246
	v_lshlrev_b32_e32 v214, 16, v247
	v_and_b32_e32 v215, 0xffff0000, v247
	v_pk_fma_f32 v[62:63], v[62:63], 0.5, v[208:209] op_sel_hi:[1,0,1]
	v_pk_fma_f32 v[60:61], v[60:61], 0.5, v[194:195] op_sel_hi:[1,0,1]
	v_pk_fma_f32 v[58:59], v[58:59], 0.5, v[210:211] op_sel_hi:[1,0,1]
	v_pk_fma_f32 v[56:57], v[56:57], 0.5, v[216:217] op_sel_hi:[1,0,1]
	v_pk_fma_f32 v[54:55], v[54:55], 0.5, v[212:213] op_sel_hi:[1,0,1]
	v_pk_fma_f32 v[52:53], v[52:53], 0.5, v[218:219] op_sel_hi:[1,0,1]
	v_pk_fma_f32 v[50:51], v[50:51], 0.5, v[214:215] op_sel_hi:[1,0,1]
	v_pk_fma_f32 v[48:49], v[48:49], 0.5, v[220:221] op_sel_hi:[1,0,1]
	v_mul_f32_e32 v194, v61, v61
	v_mul_f32_e32 v195, v63, v63
	v_mul_f32_e32 v207, v57, v57
	v_mul_f32_e32 v208, v59, v59
	v_mul_f32_e32 v209, v53, v53
	v_mul_f32_e32 v210, v55, v55
	v_mul_f32_e32 v211, v49, v49
	v_mul_f32_e32 v212, v51, v51
	v_fmac_f32_e32 v194, v60, v60
	v_fmac_f32_e32 v195, v62, v62
	v_fmac_f32_e32 v207, v56, v56
	v_fmac_f32_e32 v208, v58, v58
	v_fmac_f32_e32 v209, v52, v52
	v_fmac_f32_e32 v210, v54, v54
	v_fmac_f32_e32 v211, v48, v48
	v_fmac_f32_e32 v212, v50, v50
	v_add_f32_e32 v194, v194, v195
	v_add_f32_e32 v195, v207, v208
	v_add_f32_e32 v207, v209, v210
	v_add_f32_e32 v208, v211, v212
	v_add_f32_e32 v194, v194, v195
	v_add_f32_e32 v195, v207, v208
	v_add_f32_e32 v194, v194, v195
	v_mov_b32_e32 v236, v194
	v_mov_b32_e32 v237, v194
	s_nop 1
	v_permlane16_swap_b32_e32 v236, v237
	v_cndmask_b32_e64 v195, v237, v236, s[98:99]
	s_waitcnt lgkmcnt(0)
	v_add_f32_e32 v207, v194, v195
	v_mov_b32_e32 v236, v207
	v_mov_b32_e32 v237, v207
	s_nop 1
	v_permlane32_swap_b32_e32 v236, v237
	v_cndmask_b32_e64 v208, v237, v236, s[100:101]
	v_lshlrev_b64 v[194:195], 6, v[184:185]
	s_and_saveexec_b64 s[20:21], s[0:1]
	s_cbranch_execz .LBB0_1190
	s_waitcnt lgkmcnt(0)
	v_add_f32_e32 v207, v207, v208
	v_lshl_add_u64 v[208:209], s[2:3], 0, v[194:195]
	global_store_dword v[208:209], v207, off
.LBB0_1190:
	s_or_b64 exec, exec, s[20:21]
	s_waitcnt vmcnt(5) lgkmcnt(0)
	v_lshlrev_b32_e32 v208, 16, v248
	v_and_b32_e32 v209, 0xffff0000, v248
	v_lshlrev_b32_e32 v84, 16, v249
	v_and_b32_e32 v85, 0xffff0000, v249
	v_pk_fma_f32 v[46:47], v[46:47], 0.5, v[84:85] op_sel_hi:[1,0,1]
	v_pk_fma_f32 v[44:45], v[44:45], 0.5, v[208:209] op_sel_hi:[1,0,1]
	v_lshlrev_b32_e32 v84, 16, v250
	v_and_b32_e32 v85, 0xffff0000, v250
	v_lshlrev_b32_e32 v86, 16, v251
	v_and_b32_e32 v87, 0xffff0000, v251
	v_pk_fma_f32 v[40:41], v[40:41], 0.5, v[84:85] op_sel_hi:[1,0,1]
	v_mul_f32_e32 v84, v45, v45
	v_mul_f32_e32 v85, v47, v47
	v_pk_fma_f32 v[42:43], v[42:43], 0.5, v[86:87] op_sel_hi:[1,0,1]
	v_fmac_f32_e32 v84, v44, v44
	v_fmac_f32_e32 v85, v46, v46
	v_add_f32_e32 v84, v84, v85
	v_mul_f32_e32 v85, v41, v41
	v_mul_f32_e32 v86, v43, v43
	v_fmac_f32_e32 v85, v40, v40
	v_fmac_f32_e32 v86, v42, v42
	v_add_f32_e32 v85, v85, v86
	v_add_f32_e32 v86, v84, v85
	s_waitcnt vmcnt(4)
	v_lshlrev_b32_e32 v84, 16, v252
	v_and_b32_e32 v85, 0xffff0000, v252
	v_lshlrev_b32_e32 v80, 16, v253
	v_and_b32_e32 v81, 0xffff0000, v253
	v_pk_fma_f32 v[38:39], v[38:39], 0.5, v[80:81] op_sel_hi:[1,0,1]
	v_pk_fma_f32 v[36:37], v[36:37], 0.5, v[84:85] op_sel_hi:[1,0,1]
	v_lshlrev_b32_e32 v80, 16, v254
	v_and_b32_e32 v81, 0xffff0000, v254
	v_lshlrev_b32_e32 v82, 16, v255
	v_and_b32_e32 v83, 0xffff0000, v255
	v_pk_fma_f32 v[32:33], v[32:33], 0.5, v[80:81] op_sel_hi:[1,0,1]
	v_mul_f32_e32 v80, v37, v37
	v_mul_f32_e32 v81, v39, v39
	v_pk_fma_f32 v[34:35], v[34:35], 0.5, v[82:83] op_sel_hi:[1,0,1]
	v_fmac_f32_e32 v80, v36, v36
	v_fmac_f32_e32 v81, v38, v38
	v_add_f32_e32 v80, v80, v81
	v_mul_f32_e32 v81, v33, v33
	v_mul_f32_e32 v82, v35, v35
	v_fmac_f32_e32 v81, v32, v32
	v_fmac_f32_e32 v82, v34, v34
	v_add_f32_e32 v81, v81, v82
	v_add_f32_e32 v80, v80, v81
	v_add_f32_e32 v80, v86, v80
	v_mov_b32_e32 v236, v80
	v_mov_b32_e32 v237, v80
	s_nop 1
	v_permlane16_swap_b32_e32 v236, v237
	v_cndmask_b32_e64 v81, v237, v236, s[98:99]
	s_waitcnt lgkmcnt(0)
	v_add_f32_e32 v82, v80, v81
	v_mov_b32_e32 v236, v82
	v_mov_b32_e32 v237, v82
	s_nop 1
	v_permlane32_swap_b32_e32 v236, v237
	v_cndmask_b32_e64 v83, v237, v236, s[100:101]
	v_lshlrev_b64 v[80:81], 6, v[128:129]
	s_and_saveexec_b64 s[20:21], s[0:1]
	s_cbranch_execz .LBB0_1192
	s_waitcnt lgkmcnt(0)
	v_add_f32_e32 v84, v82, v83
	v_lshl_add_u64 v[82:83], s[2:3], 0, v[80:81]
	global_store_dword v[82:83], v84, off
